# loop-edge edit: K-loop counter/address increments + exit compare moved from the loop head into the previous load segment (5 GEMM loops), on top of astat order + unscaled MFMA + handoff edits
# baseline (speedup 1.0000x reference)
.LBB0_198:
	ds_read_b128 v[2:5], v190
	ds_read_b128 v[6:9], v190 offset:1024
	ds_read_b128 v[18:21], v190 offset:2048
	ds_read_b128 v[22:25], v190 offset:3072
	ds_read_b128 v[26:29], v190 offset:16384
	ds_read_b128 v[30:33], v190 offset:17408
	ds_read_b128 v[180:183], v190 offset:18432
	ds_read_b128 v[184:187], v190 offset:19456
	s_add_u32 s54, s72, 0xfff80080
	s_addc_u32 s55, s73, -1
	s_cmp_eq_u32 s62, 28
	s_cselect_b32 s75, s47, s55
	s_cselect_b32 s74, s70, s54
	s_cselect_b32 s55, s45, s9
	s_cselect_b32 s54, s71, s8
	s_mov_b32 m0, s92
	v_lshl_add_u64 v[216:217], s[72:73], 0, v[172:173]
	ds_read_b128 v[10:13], v191
	ds_read_b128 v[14:17], v191 offset:1024
	ds_read_b128 v[192:195], v191 offset:2048
	ds_read_b128 v[196:199], v191 offset:3072
	ds_read_b128 v[200:203], v191 offset:4096
	ds_read_b128 v[204:207], v191 offset:5120
	ds_read_b128 v[208:211], v191 offset:6144
	ds_read_b128 v[212:215], v191 offset:7168
	global_load_lds_dwordx4 v[216:217], off
	v_lshl_add_u64 v[216:217], s[72:73], 0, v[174:175]
	s_mov_b32 m0, s93
	s_nop 0
	global_load_lds_dwordx4 v[216:217], off
	s_waitcnt vmcnt(8)
	s_waitcnt lgkmcnt(0)
	s_setprio 1
	s_barrier
	v_mfma_f32_16x16x128_f8f6f4 v[158:161], v[2:9], v[10:17], v[158:161]
	v_mfma_f32_16x16x128_f8f6f4 v[154:157], v[18:25], v[10:17], v[154:157]
	v_mfma_f32_16x16x128_f8f6f4 v[122:125], v[180:187], v[10:17], v[122:125]
	v_mfma_f32_16x16x128_f8f6f4 v[126:129], v[26:33], v[10:17], v[126:129]
	v_mfma_f32_16x16x128_f8f6f4 v[118:121], v[26:33], v[192:199], v[118:121]
	v_mfma_f32_16x16x128_f8f6f4 v[114:117], v[180:187], v[192:199], v[114:117]
	v_mfma_f32_16x16x128_f8f6f4 v[146:149], v[18:25], v[192:199], v[146:149]
	v_mfma_f32_16x16x128_f8f6f4 v[150:153], v[2:9], v[192:199], v[150:153]
	s_setprio 0
	s_setprio 1
	v_mfma_f32_16x16x128_f8f6f4 v[142:145], v[2:9], v[200:207], v[142:145]
	v_mfma_f32_16x16x128_f8f6f4 v[138:141], v[18:25], v[200:207], v[138:141]
	v_mfma_f32_16x16x128_f8f6f4 v[106:109], v[180:187], v[200:207], v[106:109]
	v_mfma_f32_16x16x128_f8f6f4 v[110:113], v[26:33], v[200:207], v[110:113]
	v_mfma_f32_16x16x128_f8f6f4 v[102:105], v[26:33], v[208:215], v[102:105]
	v_mfma_f32_16x16x128_f8f6f4 v[98:101], v[180:187], v[208:215], v[98:101]
	v_mfma_f32_16x16x128_f8f6f4 v[130:133], v[18:25], v[208:215], v[130:133]
	v_mfma_f32_16x16x128_f8f6f4 v[134:137], v[2:9], v[208:215], v[134:137]
	s_barrier
	s_setprio 0
	s_mov_b32 m0, s77
	v_lshl_add_u64 v[10:11], s[54:55], 0, v[166:167]
	s_add_u32 vcc_lo, s54, 0x80000
	ds_read_b128 v[192:195], v191 offset:16384
	ds_read_b128 v[196:199], v191 offset:17408
	ds_read_b128 v[200:203], v191 offset:18432
	ds_read_b128 v[204:207], v191 offset:19456
	ds_read_b128 v[208:211], v191 offset:20480
	ds_read_b128 v[212:215], v191 offset:21504
	ds_read_b128 v[216:219], v191 offset:22528
	ds_read_b128 v[220:223], v191 offset:23552
	global_load_lds_dwordx4 v[10:11], off
	v_lshl_add_u64 v[12:13], s[54:55], 0, v[170:171]
	s_mov_b32 m0, s78
	s_addc_u32 vcc_hi, s55, 0
	global_load_lds_dwordx4 v[12:13], off
	v_lshl_add_u64 v[14:15], vcc, 0, v[166:167]
	s_mov_b32 m0, s79
	v_lshl_add_u64 v[16:17], s[74:75], 0, v[168:169]
	global_load_lds_dwordx4 v[14:15], off
	v_lshl_add_u64 v[14:15], vcc, 0, v[170:171]
	s_mov_b32 m0, s80
	s_nop 0
	global_load_lds_dwordx4 v[14:15], off
	v_lshl_add_u64 v[14:15], s[74:75], 0, v[164:165]
	s_mov_b32 m0, s53
	s_nop 0
	global_load_lds_dwordx4 v[14:15], off
	s_mov_b32 m0, s81
	s_nop 0
	global_load_lds_dwordx4 v[16:17], off
	s_waitcnt vmcnt(8)
	s_waitcnt lgkmcnt(0)
	s_setprio 1
	s_barrier
	v_mfma_f32_16x16x128_f8f6f4 v[94:97], v[2:9], v[192:199], v[94:97]
	v_mfma_f32_16x16x128_f8f6f4 v[90:93], v[18:25], v[192:199], v[90:93]
	v_mfma_f32_16x16x128_f8f6f4 v[58:61], v[180:187], v[192:199], v[58:61]
	v_mfma_f32_16x16x128_f8f6f4 v[62:65], v[26:33], v[192:199], v[62:65]
	v_mfma_f32_16x16x128_f8f6f4 v[54:57], v[26:33], v[200:207], v[54:57]
	v_mfma_f32_16x16x128_f8f6f4 v[50:53], v[180:187], v[200:207], v[50:53]
	v_mfma_f32_16x16x128_f8f6f4 v[82:85], v[18:25], v[200:207], v[82:85]
	v_mfma_f32_16x16x128_f8f6f4 v[86:89], v[2:9], v[200:207], v[86:89]
	s_setprio 0
	s_setprio 1
	v_mfma_f32_16x16x128_f8f6f4 v[78:81], v[2:9], v[208:215], v[78:81]
	v_mfma_f32_16x16x128_f8f6f4 v[74:77], v[18:25], v[208:215], v[74:77]
	v_mfma_f32_16x16x128_f8f6f4 v[42:45], v[180:187], v[208:215], v[42:45]
	v_mfma_f32_16x16x128_f8f6f4 v[46:49], v[26:33], v[208:215], v[46:49]
	v_mfma_f32_16x16x128_f8f6f4 v[38:41], v[26:33], v[216:223], v[38:41]
	v_mfma_f32_16x16x128_f8f6f4 v[34:37], v[180:187], v[216:223], v[34:37]
	v_mfma_f32_16x16x128_f8f6f4 v[66:69], v[18:25], v[216:223], v[66:69]
	v_mfma_f32_16x16x128_f8f6f4 v[70:73], v[2:9], v[216:223], v[70:73]
	s_barrier
	s_setprio 0
	ds_read_b128 v[18:21], v190 offset:32768
	ds_read_b128 v[22:25], v190 offset:33792
	ds_read_b128 v[26:29], v190 offset:34816
	ds_read_b128 v[30:33], v190 offset:35840
	ds_read_b128 v[2:5], v190 offset:49152
	ds_read_b128 v[6:9], v190 offset:50176
	ds_read_b128 v[180:183], v190 offset:51200
	ds_read_b128 v[184:187], v190 offset:52224
	s_add_u32 s74, s74, 0x80000
	s_addc_u32 s75, s75, 0
	s_mov_b32 m0, s82
	v_lshl_add_u64 v[224:225], s[74:75], 0, v[164:165]
	ds_read_b128 v[192:195], v191 offset:32768
	ds_read_b128 v[196:199], v191 offset:33792
	ds_read_b128 v[200:203], v191 offset:34816
	ds_read_b128 v[204:207], v191 offset:35840
	ds_read_b128 v[208:211], v191 offset:36864
	ds_read_b128 v[212:215], v191 offset:37888
	ds_read_b128 v[216:219], v191 offset:38912
	ds_read_b128 v[220:223], v191 offset:39936
	global_load_lds_dwordx4 v[224:225], off
	v_lshl_add_u64 v[224:225], s[74:75], 0, v[168:169]
	s_mov_b32 m0, s83
	s_nop 0
	global_load_lds_dwordx4 v[224:225], off
	s_waitcnt vmcnt(8)
	s_waitcnt lgkmcnt(0)
	s_setprio 1
	s_barrier
	v_mfma_f32_16x16x128_f8f6f4 v[158:161], v[18:25], v[192:199], v[158:161]
	v_mfma_f32_16x16x128_f8f6f4 v[154:157], v[26:33], v[192:199], v[154:157]
	v_mfma_f32_16x16x128_f8f6f4 v[122:125], v[180:187], v[192:199], v[122:125]
	v_mfma_f32_16x16x128_f8f6f4 v[126:129], v[2:9], v[192:199], v[126:129]
	v_mfma_f32_16x16x128_f8f6f4 v[118:121], v[2:9], v[200:207], v[118:121]
	v_mfma_f32_16x16x128_f8f6f4 v[114:117], v[180:187], v[200:207], v[114:117]
	v_mfma_f32_16x16x128_f8f6f4 v[146:149], v[26:33], v[200:207], v[146:149]
	v_mfma_f32_16x16x128_f8f6f4 v[150:153], v[18:25], v[200:207], v[150:153]
	s_setprio 0
	s_setprio 1
	v_mfma_f32_16x16x128_f8f6f4 v[142:145], v[18:25], v[208:215], v[142:145]
	v_mfma_f32_16x16x128_f8f6f4 v[138:141], v[26:33], v[208:215], v[138:141]
	v_mfma_f32_16x16x128_f8f6f4 v[106:109], v[180:187], v[208:215], v[106:109]
	v_mfma_f32_16x16x128_f8f6f4 v[110:113], v[2:9], v[208:215], v[110:113]
	v_mfma_f32_16x16x128_f8f6f4 v[102:105], v[2:9], v[216:223], v[102:105]
	v_mfma_f32_16x16x128_f8f6f4 v[98:101], v[180:187], v[216:223], v[98:101]
	v_mfma_f32_16x16x128_f8f6f4 v[130:133], v[26:33], v[216:223], v[130:133]
	v_mfma_f32_16x16x128_f8f6f4 v[134:137], v[18:25], v[216:223], v[134:137]
	s_barrier
	s_setprio 0
	s_mov_b32 m0, s86
	v_lshl_add_u64 v[10:11], v[10:11], 0, s[4:5]
	s_add_u32 s54, s54, 0x80080
	ds_read_b128 v[192:195], v191 offset:49152
	ds_read_b128 v[196:199], v191 offset:50176
	ds_read_b128 v[200:203], v191 offset:51200
	ds_read_b128 v[204:207], v191 offset:52224
	ds_read_b128 v[208:211], v191 offset:53248
	ds_read_b128 v[212:215], v191 offset:54272
	ds_read_b128 v[216:219], v191 offset:55296
	ds_read_b128 v[220:223], v191 offset:56320
	global_load_lds_dwordx4 v[10:11], off
	v_lshl_add_u64 v[10:11], v[12:13], 0, s[4:5]
	s_mov_b32 m0, s87
	s_addc_u32 s55, s55, 0
	global_load_lds_dwordx4 v[10:11], off
	v_lshl_add_u64 v[10:11], s[54:55], 0, v[166:167]
	s_mov_b32 m0, s90
	s_nop 0
	global_load_lds_dwordx4 v[10:11], off
	v_lshl_add_u64 v[10:11], s[54:55], 0, v[170:171]
	s_mov_b32 m0, s91
	s_nop 0
	global_load_lds_dwordx4 v[10:11], off
	v_lshl_add_u64 v[10:11], v[14:15], 0, s[4:5]
	s_mov_b32 m0, s88
	s_nop 0
	global_load_lds_dwordx4 v[10:11], off
	v_lshl_add_u64 v[10:11], v[16:17], 0, s[4:5]
	s_mov_b32 m0, s89
	s_nop 0
	global_load_lds_dwordx4 v[10:11], off
	s_add_i32 s62, s62, 2
	s_add_u32 s72, s72, 0x100
	s_addc_u32 s73, s73, 0
	s_add_u32 s8, s8, 0x100
	s_addc_u32 s9, s9, 0
	s_cmp_gt_u32 s62, 29
	s_waitcnt vmcnt(8)
	s_waitcnt lgkmcnt(0)
	s_setprio 1
	s_barrier
	v_mfma_f32_16x16x128_f8f6f4 v[94:97], v[18:25], v[192:199], v[94:97]
	v_mfma_f32_16x16x128_f8f6f4 v[90:93], v[26:33], v[192:199], v[90:93]
	v_mfma_f32_16x16x128_f8f6f4 v[58:61], v[180:187], v[192:199], v[58:61]
	v_mfma_f32_16x16x128_f8f6f4 v[62:65], v[2:9], v[192:199], v[62:65]
	v_mfma_f32_16x16x128_f8f6f4 v[54:57], v[2:9], v[200:207], v[54:57]
	v_mfma_f32_16x16x128_f8f6f4 v[50:53], v[180:187], v[200:207], v[50:53]
	v_mfma_f32_16x16x128_f8f6f4 v[82:85], v[26:33], v[200:207], v[82:85]
	v_mfma_f32_16x16x128_f8f6f4 v[86:89], v[18:25], v[200:207], v[86:89]
	s_setprio 0
	s_setprio 1
	v_mfma_f32_16x16x128_f8f6f4 v[78:81], v[18:25], v[208:215], v[78:81]
	v_mfma_f32_16x16x128_f8f6f4 v[74:77], v[26:33], v[208:215], v[74:77]
	v_mfma_f32_16x16x128_f8f6f4 v[42:45], v[180:187], v[208:215], v[42:45]
	v_mfma_f32_16x16x128_f8f6f4 v[46:49], v[2:9], v[208:215], v[46:49]
	v_mfma_f32_16x16x128_f8f6f4 v[38:41], v[2:9], v[216:223], v[38:41]
	v_mfma_f32_16x16x128_f8f6f4 v[34:37], v[180:187], v[216:223], v[34:37]
	v_mfma_f32_16x16x128_f8f6f4 v[66:69], v[26:33], v[216:223], v[66:69]
	v_mfma_f32_16x16x128_f8f6f4 v[70:73], v[18:25], v[216:223], v[70:73]
	s_barrier
	s_setprio 0
	s_cbranch_scc0 .LBB0_198
	s_and_b64 vcc, exec, s[6:7]
	s_cbranch_vccz .LBB0_201
	s_barrier

.LBB0_438:
	ds_read_b128 v[2:5], v200
	ds_read_b128 v[6:9], v200 offset:1024
	ds_read_b128 v[18:21], v200 offset:2048
	ds_read_b128 v[22:25], v200 offset:3072
	ds_read_b128 v[26:29], v200 offset:16384
	ds_read_b128 v[30:33], v200 offset:17408
	ds_read_b128 v[180:183], v200 offset:18432
	ds_read_b128 v[184:187], v200 offset:19456
	s_add_u32 s54, s72, 0xfff80080
	s_addc_u32 s55, s73, -1
	s_cmp_eq_u32 s62, 28
	s_cselect_b32 s75, s47, s55
	s_cselect_b32 s74, s71, s54
	s_cselect_b32 s55, s45, s9
	s_cselect_b32 s54, s94, s8
	s_mov_b32 m0, s33
	v_lshl_add_u64 v[226:227], s[72:73], 0, v[170:171]
	ds_read_b128 v[10:13], v201
	ds_read_b128 v[14:17], v201 offset:1024
	ds_read_b128 v[202:205], v201 offset:2048
	ds_read_b128 v[206:209], v201 offset:3072
	ds_read_b128 v[210:213], v201 offset:4096
	ds_read_b128 v[214:217], v201 offset:5120
	ds_read_b128 v[218:221], v201 offset:6144
	ds_read_b128 v[222:225], v201 offset:7168
	global_load_lds_dwordx4 v[226:227], off
	v_lshl_add_u64 v[226:227], s[72:73], 0, v[172:173]
	s_mov_b32 m0, s93
	s_nop 0
	global_load_lds_dwordx4 v[226:227], off
	s_waitcnt vmcnt(8)
	s_waitcnt lgkmcnt(0)
	s_setprio 1
	s_barrier
	v_mfma_f32_16x16x128_f8f6f4 v[158:161], v[2:9], v[10:17], v[158:161]
	v_mfma_f32_16x16x128_f8f6f4 v[154:157], v[18:25], v[10:17], v[154:157]
	v_mfma_f32_16x16x128_f8f6f4 v[122:125], v[180:187], v[10:17], v[122:125]
	v_mfma_f32_16x16x128_f8f6f4 v[126:129], v[26:33], v[10:17], v[126:129]
	v_mfma_f32_16x16x128_f8f6f4 v[118:121], v[26:33], v[202:209], v[118:121]
	v_mfma_f32_16x16x128_f8f6f4 v[114:117], v[180:187], v[202:209], v[114:117]
	v_mfma_f32_16x16x128_f8f6f4 v[146:149], v[18:25], v[202:209], v[146:149]
	v_mfma_f32_16x16x128_f8f6f4 v[150:153], v[2:9], v[202:209], v[150:153]
	s_setprio 0
	s_setprio 1
	v_mfma_f32_16x16x128_f8f6f4 v[142:145], v[2:9], v[210:217], v[142:145]
	v_mfma_f32_16x16x128_f8f6f4 v[138:141], v[18:25], v[210:217], v[138:141]
	v_mfma_f32_16x16x128_f8f6f4 v[106:109], v[180:187], v[210:217], v[106:109]
	v_mfma_f32_16x16x128_f8f6f4 v[110:113], v[26:33], v[210:217], v[110:113]
	v_mfma_f32_16x16x128_f8f6f4 v[102:105], v[26:33], v[218:225], v[102:105]
	v_mfma_f32_16x16x128_f8f6f4 v[98:101], v[180:187], v[218:225], v[98:101]
	v_mfma_f32_16x16x128_f8f6f4 v[130:133], v[18:25], v[218:225], v[130:133]
	v_mfma_f32_16x16x128_f8f6f4 v[134:137], v[2:9], v[218:225], v[134:137]
	s_barrier
	s_setprio 0
	s_mov_b32 m0, s78
	v_lshl_add_u64 v[10:11], s[54:55], 0, v[164:165]
	s_add_u32 s96, s54, 0x80000
	ds_read_b128 v[202:205], v201 offset:16384
	ds_read_b128 v[206:209], v201 offset:17408
	ds_read_b128 v[210:213], v201 offset:18432
	ds_read_b128 v[214:217], v201 offset:19456
	ds_read_b128 v[218:221], v201 offset:20480
	ds_read_b128 v[222:225], v201 offset:21504
	ds_read_b128 v[226:229], v201 offset:22528
	ds_read_b128 v[230:233], v201 offset:23552
	global_load_lds_dwordx4 v[10:11], off
	v_lshl_add_u64 v[12:13], s[54:55], 0, v[168:169]
	s_mov_b32 m0, s79
	s_addc_u32 s97, s55, 0
	global_load_lds_dwordx4 v[12:13], off
	v_lshl_add_u64 v[14:15], s[96:97], 0, v[164:165]
	s_mov_b32 m0, s80
	v_lshl_add_u64 v[16:17], s[74:75], 0, v[166:167]
	global_load_lds_dwordx4 v[14:15], off
	v_lshl_add_u64 v[14:15], s[96:97], 0, v[168:169]
	s_mov_b32 m0, s81
	s_nop 0
	global_load_lds_dwordx4 v[14:15], off
	v_lshl_add_u64 v[14:15], s[74:75], 0, v[162:163]
	s_mov_b32 m0, s53
	s_nop 0
	global_load_lds_dwordx4 v[14:15], off
	s_mov_b32 m0, s82
	s_nop 0
	global_load_lds_dwordx4 v[16:17], off
	s_waitcnt vmcnt(8)
	s_waitcnt lgkmcnt(0)
	s_setprio 1
	s_barrier
	v_mfma_f32_16x16x128_f8f6f4 v[94:97], v[2:9], v[202:209], v[94:97]
	v_mfma_f32_16x16x128_f8f6f4 v[90:93], v[18:25], v[202:209], v[90:93]
	v_mfma_f32_16x16x128_f8f6f4 v[58:61], v[180:187], v[202:209], v[58:61]
	v_mfma_f32_16x16x128_f8f6f4 v[62:65], v[26:33], v[202:209], v[62:65]
	v_mfma_f32_16x16x128_f8f6f4 v[54:57], v[26:33], v[210:217], v[54:57]
	v_mfma_f32_16x16x128_f8f6f4 v[50:53], v[180:187], v[210:217], v[50:53]
	v_mfma_f32_16x16x128_f8f6f4 v[82:85], v[18:25], v[210:217], v[82:85]
	v_mfma_f32_16x16x128_f8f6f4 v[86:89], v[2:9], v[210:217], v[86:89]
	s_setprio 0
	s_setprio 1
	v_mfma_f32_16x16x128_f8f6f4 v[78:81], v[2:9], v[218:225], v[78:81]
	v_mfma_f32_16x16x128_f8f6f4 v[74:77], v[18:25], v[218:225], v[74:77]
	v_mfma_f32_16x16x128_f8f6f4 v[42:45], v[180:187], v[218:225], v[42:45]
	v_mfma_f32_16x16x128_f8f6f4 v[46:49], v[26:33], v[218:225], v[46:49]
	v_mfma_f32_16x16x128_f8f6f4 v[38:41], v[26:33], v[226:233], v[38:41]
	v_mfma_f32_16x16x128_f8f6f4 v[34:37], v[180:187], v[226:233], v[34:37]
	v_mfma_f32_16x16x128_f8f6f4 v[66:69], v[18:25], v[226:233], v[66:69]
	v_mfma_f32_16x16x128_f8f6f4 v[70:73], v[2:9], v[226:233], v[70:73]
	s_barrier
	s_setprio 0
	ds_read_b128 v[18:21], v200 offset:32768
	ds_read_b128 v[22:25], v200 offset:33792
	ds_read_b128 v[26:29], v200 offset:34816
	ds_read_b128 v[30:33], v200 offset:35840
	ds_read_b128 v[2:5], v200 offset:49152
	ds_read_b128 v[6:9], v200 offset:50176
	ds_read_b128 v[180:183], v200 offset:51200
	ds_read_b128 v[184:187], v200 offset:52224
	s_add_u32 s74, s74, 0x80000
	s_addc_u32 s75, s75, 0
	s_mov_b32 m0, s83
	v_lshl_add_u64 v[234:235], s[74:75], 0, v[162:163]
	ds_read_b128 v[202:205], v201 offset:32768
	ds_read_b128 v[206:209], v201 offset:33792
	ds_read_b128 v[210:213], v201 offset:34816
	ds_read_b128 v[214:217], v201 offset:35840
	ds_read_b128 v[218:221], v201 offset:36864
	ds_read_b128 v[222:225], v201 offset:37888
	ds_read_b128 v[226:229], v201 offset:38912
	ds_read_b128 v[230:233], v201 offset:39936
	global_load_lds_dwordx4 v[234:235], off
	v_lshl_add_u64 v[234:235], s[74:75], 0, v[166:167]
	s_mov_b32 m0, s84
	s_nop 0
	global_load_lds_dwordx4 v[234:235], off
	s_waitcnt vmcnt(8)
	s_waitcnt lgkmcnt(0)
	s_setprio 1
	s_barrier
	v_mfma_f32_16x16x128_f8f6f4 v[158:161], v[18:25], v[202:209], v[158:161]
	v_mfma_f32_16x16x128_f8f6f4 v[154:157], v[26:33], v[202:209], v[154:157]
	v_mfma_f32_16x16x128_f8f6f4 v[122:125], v[180:187], v[202:209], v[122:125]
	v_mfma_f32_16x16x128_f8f6f4 v[126:129], v[2:9], v[202:209], v[126:129]
	v_mfma_f32_16x16x128_f8f6f4 v[118:121], v[2:9], v[210:217], v[118:121]
	v_mfma_f32_16x16x128_f8f6f4 v[114:117], v[180:187], v[210:217], v[114:117]
	v_mfma_f32_16x16x128_f8f6f4 v[146:149], v[26:33], v[210:217], v[146:149]
	v_mfma_f32_16x16x128_f8f6f4 v[150:153], v[18:25], v[210:217], v[150:153]
	s_setprio 0
	s_setprio 1
	v_mfma_f32_16x16x128_f8f6f4 v[142:145], v[18:25], v[218:225], v[142:145]
	v_mfma_f32_16x16x128_f8f6f4 v[138:141], v[26:33], v[218:225], v[138:141]
	v_mfma_f32_16x16x128_f8f6f4 v[106:109], v[180:187], v[218:225], v[106:109]
	v_mfma_f32_16x16x128_f8f6f4 v[110:113], v[2:9], v[218:225], v[110:113]
	v_mfma_f32_16x16x128_f8f6f4 v[102:105], v[2:9], v[226:233], v[102:105]
	v_mfma_f32_16x16x128_f8f6f4 v[98:101], v[180:187], v[226:233], v[98:101]
	v_mfma_f32_16x16x128_f8f6f4 v[130:133], v[26:33], v[226:233], v[130:133]
	v_mfma_f32_16x16x128_f8f6f4 v[134:137], v[18:25], v[226:233], v[134:137]
	s_barrier
	s_setprio 0
	s_mov_b32 m0, s87
	v_lshl_add_u64 v[10:11], v[10:11], 0, s[4:5]
	s_add_u32 s54, s54, 0x80080
	ds_read_b128 v[202:205], v201 offset:49152
	ds_read_b128 v[206:209], v201 offset:50176
	ds_read_b128 v[210:213], v201 offset:51200
	ds_read_b128 v[214:217], v201 offset:52224
	ds_read_b128 v[218:221], v201 offset:53248
	ds_read_b128 v[222:225], v201 offset:54272
	ds_read_b128 v[226:229], v201 offset:55296
	ds_read_b128 v[230:233], v201 offset:56320
	global_load_lds_dwordx4 v[10:11], off
	v_lshl_add_u64 v[10:11], v[12:13], 0, s[4:5]
	s_mov_b32 m0, s88
	s_addc_u32 s55, s55, 0
	global_load_lds_dwordx4 v[10:11], off
	v_lshl_add_u64 v[10:11], s[54:55], 0, v[164:165]
	s_mov_b32 m0, s91
	s_nop 0
	global_load_lds_dwordx4 v[10:11], off
	v_lshl_add_u64 v[10:11], s[54:55], 0, v[168:169]
	s_mov_b32 m0, s92
	s_nop 0
	global_load_lds_dwordx4 v[10:11], off
	v_lshl_add_u64 v[10:11], v[14:15], 0, s[4:5]
	s_mov_b32 m0, s89
	s_nop 0
	global_load_lds_dwordx4 v[10:11], off
	v_lshl_add_u64 v[10:11], v[16:17], 0, s[4:5]
	s_mov_b32 m0, s90
	s_nop 0
	global_load_lds_dwordx4 v[10:11], off
	s_add_i32 s62, s62, 2
	s_add_u32 s72, s72, 0x100
	s_addc_u32 s73, s73, 0
	s_add_u32 s8, s8, 0x100
	s_addc_u32 s9, s9, 0
	s_cmp_gt_u32 s62, 29
	s_waitcnt vmcnt(8)
	s_waitcnt lgkmcnt(0)
	s_setprio 1
	s_barrier
	v_mfma_f32_16x16x128_f8f6f4 v[94:97], v[18:25], v[202:209], v[94:97]
	v_mfma_f32_16x16x128_f8f6f4 v[90:93], v[26:33], v[202:209], v[90:93]
	v_mfma_f32_16x16x128_f8f6f4 v[58:61], v[180:187], v[202:209], v[58:61]
	v_mfma_f32_16x16x128_f8f6f4 v[62:65], v[2:9], v[202:209], v[62:65]
	v_mfma_f32_16x16x128_f8f6f4 v[54:57], v[2:9], v[210:217], v[54:57]
	v_mfma_f32_16x16x128_f8f6f4 v[50:53], v[180:187], v[210:217], v[50:53]
	v_mfma_f32_16x16x128_f8f6f4 v[82:85], v[26:33], v[210:217], v[82:85]
	v_mfma_f32_16x16x128_f8f6f4 v[86:89], v[18:25], v[210:217], v[86:89]
	s_setprio 0
	s_setprio 1
	v_mfma_f32_16x16x128_f8f6f4 v[78:81], v[18:25], v[218:225], v[78:81]
	v_mfma_f32_16x16x128_f8f6f4 v[74:77], v[26:33], v[218:225], v[74:77]
	v_mfma_f32_16x16x128_f8f6f4 v[42:45], v[180:187], v[218:225], v[42:45]
	v_mfma_f32_16x16x128_f8f6f4 v[46:49], v[2:9], v[218:225], v[46:49]
	v_mfma_f32_16x16x128_f8f6f4 v[38:41], v[2:9], v[226:233], v[38:41]
	v_mfma_f32_16x16x128_f8f6f4 v[34:37], v[180:187], v[226:233], v[34:37]
	v_mfma_f32_16x16x128_f8f6f4 v[66:69], v[26:33], v[226:233], v[66:69]
	v_mfma_f32_16x16x128_f8f6f4 v[70:73], v[18:25], v[226:233], v[70:73]
	s_barrier
	s_setprio 0
	s_cbranch_scc0 .LBB0_438
	s_and_b64 vcc, exec, s[6:7]
	s_cbranch_vccz .LBB0_441
	s_barrier

.LBB0_452:
	ds_read_b128 v[146:149], v143
	ds_read_b128 v[150:153], v143 offset:1024
	ds_read_b128 v[154:157], v143 offset:2048
	ds_read_b128 v[158:161], v143 offset:3072
	ds_read_b128 v[162:165], v143 offset:16384
	ds_read_b128 v[166:169], v143 offset:17408
	ds_read_b128 v[170:173], v143 offset:18432
	ds_read_b128 v[174:177], v143 offset:19456
	s_add_u32 s8, s52, 0xfff00080
	s_addc_u32 s9, s53, -1
	s_cmp_eq_u32 s91, 28
	s_cselect_b32 s73, s27, s9
	s_cselect_b32 s72, s37, s8
	s_cselect_b32 s55, s39, s90
	s_cselect_b32 s54, s45, s89
	v_lshl_add_u64 v[140:141], s[52:53], 0, v[136:137]
	s_add_i32 m0, s47, 0xc000
	ds_read_b128 v[180:183], v144
	ds_read_b128 v[184:187], v144 offset:1024
	ds_read_b128 v[188:191], v144 offset:2048
	ds_read_b128 v[192:195], v144 offset:3072
	ds_read_b128 v[196:199], v144 offset:4096
	ds_read_b128 v[200:203], v144 offset:5120
	ds_read_b128 v[204:207], v144 offset:6144
	ds_read_b128 v[208:211], v144 offset:7168
	global_load_lds_dwordx4 v[140:141], off
	v_lshl_add_u64 v[140:141], s[52:53], 0, v[138:139]
	s_add_i32 m0, s47, 0xe000
	s_nop 0
	global_load_lds_dwordx4 v[140:141], off
	s_waitcnt vmcnt(8)
	s_waitcnt lgkmcnt(0)
	s_setprio 1
	s_barrier
	v_mfma_f32_16x16x32_bf16 v[126:129], v[146:149], v[180:183], v[126:129]
	v_mfma_f32_16x16x32_bf16 v[122:125], v[154:157], v[180:183], v[122:125]
	v_mfma_f32_16x16x32_bf16 v[118:121], v[146:149], v[188:191], v[118:121]
	v_mfma_f32_16x16x32_bf16 v[114:117], v[154:157], v[188:191], v[114:117]
	v_mfma_f32_16x16x32_bf16 v[110:113], v[146:149], v[196:199], v[110:113]
	v_mfma_f32_16x16x32_bf16 v[106:109], v[154:157], v[196:199], v[106:109]
	v_mfma_f32_16x16x32_bf16 v[102:105], v[146:149], v[204:207], v[102:105]
	v_mfma_f32_16x16x32_bf16 v[98:101], v[154:157], v[204:207], v[98:101]
	v_mfma_f32_16x16x32_bf16 v[126:129], v[150:153], v[184:187], v[126:129]
	v_mfma_f32_16x16x32_bf16 v[122:125], v[158:161], v[184:187], v[122:125]
	v_mfma_f32_16x16x32_bf16 v[118:121], v[150:153], v[192:195], v[118:121]
	v_mfma_f32_16x16x32_bf16 v[114:117], v[158:161], v[192:195], v[114:117]
	v_mfma_f32_16x16x32_bf16 v[110:113], v[150:153], v[200:203], v[110:113]
	v_mfma_f32_16x16x32_bf16 v[106:109], v[158:161], v[200:203], v[106:109]
	v_mfma_f32_16x16x32_bf16 v[102:105], v[150:153], v[208:211], v[102:105]
	v_mfma_f32_16x16x32_bf16 v[98:101], v[158:161], v[208:211], v[98:101]
	s_setprio 0
	s_setprio 1
	v_mfma_f32_16x16x32_bf16 v[90:93], v[162:165], v[180:183], v[90:93]
	v_mfma_f32_16x16x32_bf16 v[82:85], v[170:173], v[180:183], v[82:85]
	v_mfma_f32_16x16x32_bf16 v[74:77], v[162:165], v[188:191], v[74:77]
	v_mfma_f32_16x16x32_bf16 v[66:69], v[170:173], v[188:191], v[66:69]
	v_mfma_f32_16x16x32_bf16 v[58:61], v[162:165], v[196:199], v[58:61]
	v_mfma_f32_16x16x32_bf16 v[50:53], v[170:173], v[196:199], v[50:53]
	v_mfma_f32_16x16x32_bf16 v[42:45], v[162:165], v[204:207], v[42:45]
	v_mfma_f32_16x16x32_bf16 v[34:37], v[170:173], v[204:207], v[34:37]
	v_mfma_f32_16x16x32_bf16 v[90:93], v[166:169], v[184:187], v[90:93]
	v_mfma_f32_16x16x32_bf16 v[82:85], v[174:177], v[184:187], v[82:85]
	v_mfma_f32_16x16x32_bf16 v[74:77], v[166:169], v[192:195], v[74:77]
	v_mfma_f32_16x16x32_bf16 v[66:69], v[174:177], v[192:195], v[66:69]
	v_mfma_f32_16x16x32_bf16 v[58:61], v[166:169], v[200:203], v[58:61]
	v_mfma_f32_16x16x32_bf16 v[50:53], v[174:177], v[200:203], v[50:53]
	v_mfma_f32_16x16x32_bf16 v[42:45], v[166:169], v[208:211], v[42:45]
	v_mfma_f32_16x16x32_bf16 v[34:37], v[174:177], v[208:211], v[34:37]
	s_barrier
	s_setprio 0
	s_mov_b32 m0, s74
	v_lshl_add_u64 v[140:141], s[54:55], 0, v[132:133]
	s_add_u32 s8, s54, 0x100000
	ds_read_b128 v[180:183], v144 offset:16384
	ds_read_b128 v[184:187], v144 offset:17408
	ds_read_b128 v[188:191], v144 offset:18432
	ds_read_b128 v[192:195], v144 offset:19456
	ds_read_b128 v[196:199], v144 offset:20480
	ds_read_b128 v[200:203], v144 offset:21504
	ds_read_b128 v[204:207], v144 offset:22528
	ds_read_b128 v[208:211], v144 offset:23552
	global_load_lds_dwordx4 v[140:141], off
	v_lshl_add_u64 v[212:213], s[54:55], 0, v[130:131]
	s_mov_b32 m0, s75
	s_addc_u32 s9, s55, 0
	global_load_lds_dwordx4 v[212:213], off
	v_lshl_add_u64 v[214:215], s[8:9], 0, v[132:133]
	s_mov_b32 m0, s76
	v_lshl_add_u64 v[216:217], s[72:73], 0, v[130:131]
	global_load_lds_dwordx4 v[214:215], off
	v_lshl_add_u64 v[214:215], s[8:9], 0, v[130:131]
	s_mov_b32 m0, s77
	s_nop 0
	global_load_lds_dwordx4 v[214:215], off
	v_lshl_add_u64 v[214:215], s[72:73], 0, v[132:133]
	s_mov_b32 m0, s47
	s_nop 0
	global_load_lds_dwordx4 v[214:215], off
	s_mov_b32 m0, s78
	s_nop 0
	global_load_lds_dwordx4 v[216:217], off
	s_waitcnt vmcnt(8)
	s_waitcnt lgkmcnt(0)
	s_setprio 1
	s_barrier
	v_mfma_f32_16x16x32_bf16 v[94:97], v[146:149], v[180:183], v[94:97]
	v_mfma_f32_16x16x32_bf16 v[86:89], v[154:157], v[180:183], v[86:89]
	v_mfma_f32_16x16x32_bf16 v[78:81], v[146:149], v[188:191], v[78:81]
	v_mfma_f32_16x16x32_bf16 v[70:73], v[154:157], v[188:191], v[70:73]
	v_mfma_f32_16x16x32_bf16 v[62:65], v[146:149], v[196:199], v[62:65]
	v_mfma_f32_16x16x32_bf16 v[54:57], v[154:157], v[196:199], v[54:57]
	v_mfma_f32_16x16x32_bf16 v[46:49], v[146:149], v[204:207], v[46:49]
	v_mfma_f32_16x16x32_bf16 v[38:41], v[154:157], v[204:207], v[38:41]
	v_mfma_f32_16x16x32_bf16 v[94:97], v[150:153], v[184:187], v[94:97]
	v_mfma_f32_16x16x32_bf16 v[86:89], v[158:161], v[184:187], v[86:89]
	v_mfma_f32_16x16x32_bf16 v[78:81], v[150:153], v[192:195], v[78:81]
	v_mfma_f32_16x16x32_bf16 v[70:73], v[158:161], v[192:195], v[70:73]
	v_mfma_f32_16x16x32_bf16 v[62:65], v[150:153], v[200:203], v[62:65]
	v_mfma_f32_16x16x32_bf16 v[54:57], v[158:161], v[200:203], v[54:57]
	v_mfma_f32_16x16x32_bf16 v[46:49], v[150:153], v[208:211], v[46:49]
	v_mfma_f32_16x16x32_bf16 v[38:41], v[158:161], v[208:211], v[38:41]
	s_setprio 0
	s_setprio 1
	v_mfma_f32_16x16x32_bf16 v[30:33], v[162:165], v[180:183], v[30:33]
	v_mfma_f32_16x16x32_bf16 v[26:29], v[170:173], v[180:183], v[26:29]
	v_mfma_f32_16x16x32_bf16 v[22:25], v[162:165], v[188:191], v[22:25]
	v_mfma_f32_16x16x32_bf16 v[18:21], v[170:173], v[188:191], v[18:21]
	v_mfma_f32_16x16x32_bf16 v[14:17], v[162:165], v[196:199], v[14:17]
	v_mfma_f32_16x16x32_bf16 v[10:13], v[170:173], v[196:199], v[10:13]
	v_mfma_f32_16x16x32_bf16 v[6:9], v[162:165], v[204:207], v[6:9]
	v_mfma_f32_16x16x32_bf16 v[2:5], v[170:173], v[204:207], v[2:5]
	v_mfma_f32_16x16x32_bf16 v[30:33], v[166:169], v[184:187], v[30:33]
	v_mfma_f32_16x16x32_bf16 v[26:29], v[174:177], v[184:187], v[26:29]
	v_mfma_f32_16x16x32_bf16 v[22:25], v[166:169], v[192:195], v[22:25]
	v_mfma_f32_16x16x32_bf16 v[18:21], v[174:177], v[192:195], v[18:21]
	v_mfma_f32_16x16x32_bf16 v[14:17], v[166:169], v[200:203], v[14:17]
	v_mfma_f32_16x16x32_bf16 v[10:13], v[174:177], v[200:203], v[10:13]
	v_mfma_f32_16x16x32_bf16 v[6:9], v[166:169], v[208:211], v[6:9]
	v_mfma_f32_16x16x32_bf16 v[2:5], v[174:177], v[208:211], v[2:5]
	s_barrier
	s_setprio 0
	ds_read_b128 v[146:149], v143 offset:32768
	ds_read_b128 v[150:153], v143 offset:33792
	ds_read_b128 v[154:157], v143 offset:34816
	ds_read_b128 v[158:161], v143 offset:35840
	ds_read_b128 v[162:165], v143 offset:49152
	ds_read_b128 v[166:169], v143 offset:50176
	ds_read_b128 v[170:173], v143 offset:51200
	ds_read_b128 v[174:177], v143 offset:52224
	s_add_u32 s8, s72, 0x100000
	s_addc_u32 s9, s73, 0
	s_mov_b32 m0, s79
	v_lshl_add_u64 v[218:219], s[8:9], 0, v[132:133]
	ds_read_b128 v[180:183], v144 offset:32768
	ds_read_b128 v[184:187], v144 offset:33792
	ds_read_b128 v[188:191], v144 offset:34816
	ds_read_b128 v[192:195], v144 offset:35840
	ds_read_b128 v[196:199], v144 offset:36864
	ds_read_b128 v[200:203], v144 offset:37888
	ds_read_b128 v[204:207], v144 offset:38912
	ds_read_b128 v[208:211], v144 offset:39936
	global_load_lds_dwordx4 v[218:219], off
	v_lshl_add_u64 v[218:219], s[8:9], 0, v[130:131]
	s_mov_b32 m0, s80
	s_nop 0
	global_load_lds_dwordx4 v[218:219], off
	s_waitcnt vmcnt(8)
	s_waitcnt lgkmcnt(0)
	s_setprio 1
	s_barrier
	v_mfma_f32_16x16x32_bf16 v[126:129], v[146:149], v[180:183], v[126:129]
	v_mfma_f32_16x16x32_bf16 v[122:125], v[154:157], v[180:183], v[122:125]
	v_mfma_f32_16x16x32_bf16 v[118:121], v[146:149], v[188:191], v[118:121]
	v_mfma_f32_16x16x32_bf16 v[114:117], v[154:157], v[188:191], v[114:117]
	v_mfma_f32_16x16x32_bf16 v[110:113], v[146:149], v[196:199], v[110:113]
	v_mfma_f32_16x16x32_bf16 v[106:109], v[154:157], v[196:199], v[106:109]
	v_mfma_f32_16x16x32_bf16 v[102:105], v[146:149], v[204:207], v[102:105]
	v_mfma_f32_16x16x32_bf16 v[98:101], v[154:157], v[204:207], v[98:101]
	v_mfma_f32_16x16x32_bf16 v[126:129], v[150:153], v[184:187], v[126:129]
	v_mfma_f32_16x16x32_bf16 v[122:125], v[158:161], v[184:187], v[122:125]
	v_mfma_f32_16x16x32_bf16 v[118:121], v[150:153], v[192:195], v[118:121]
	v_mfma_f32_16x16x32_bf16 v[114:117], v[158:161], v[192:195], v[114:117]
	v_mfma_f32_16x16x32_bf16 v[110:113], v[150:153], v[200:203], v[110:113]
	v_mfma_f32_16x16x32_bf16 v[106:109], v[158:161], v[200:203], v[106:109]
	v_mfma_f32_16x16x32_bf16 v[102:105], v[150:153], v[208:211], v[102:105]
	v_mfma_f32_16x16x32_bf16 v[98:101], v[158:161], v[208:211], v[98:101]
	s_setprio 0
	s_setprio 1
	v_mfma_f32_16x16x32_bf16 v[90:93], v[162:165], v[180:183], v[90:93]
	v_mfma_f32_16x16x32_bf16 v[82:85], v[170:173], v[180:183], v[82:85]
	v_mfma_f32_16x16x32_bf16 v[74:77], v[162:165], v[188:191], v[74:77]
	v_mfma_f32_16x16x32_bf16 v[66:69], v[170:173], v[188:191], v[66:69]
	v_mfma_f32_16x16x32_bf16 v[58:61], v[162:165], v[196:199], v[58:61]
	v_mfma_f32_16x16x32_bf16 v[50:53], v[170:173], v[196:199], v[50:53]
	v_mfma_f32_16x16x32_bf16 v[42:45], v[162:165], v[204:207], v[42:45]
	v_mfma_f32_16x16x32_bf16 v[34:37], v[170:173], v[204:207], v[34:37]
	v_mfma_f32_16x16x32_bf16 v[90:93], v[166:169], v[184:187], v[90:93]
	v_mfma_f32_16x16x32_bf16 v[82:85], v[174:177], v[184:187], v[82:85]
	v_mfma_f32_16x16x32_bf16 v[74:77], v[166:169], v[192:195], v[74:77]
	v_mfma_f32_16x16x32_bf16 v[66:69], v[174:177], v[192:195], v[66:69]
	v_mfma_f32_16x16x32_bf16 v[58:61], v[166:169], v[200:203], v[58:61]
	v_mfma_f32_16x16x32_bf16 v[50:53], v[174:177], v[200:203], v[50:53]
	v_mfma_f32_16x16x32_bf16 v[42:45], v[166:169], v[208:211], v[42:45]
	v_mfma_f32_16x16x32_bf16 v[34:37], v[174:177], v[208:211], v[34:37]
	s_barrier
	s_setprio 0
	s_mov_b32 m0, s81
	v_lshl_add_u64 v[140:141], v[140:141], 0, s[4:5]
	s_add_u32 s8, s54, 0x100080
	ds_read_b128 v[180:183], v144 offset:49152
	ds_read_b128 v[184:187], v144 offset:50176
	ds_read_b128 v[188:191], v144 offset:51200
	ds_read_b128 v[192:195], v144 offset:52224
	ds_read_b128 v[196:199], v144 offset:53248
	ds_read_b128 v[200:203], v144 offset:54272
	ds_read_b128 v[204:207], v144 offset:55296
	ds_read_b128 v[208:211], v144 offset:56320
	global_load_lds_dwordx4 v[140:141], off
	v_lshl_add_u64 v[140:141], v[212:213], 0, s[4:5]
	s_mov_b32 m0, s82
	s_addc_u32 s9, s55, 0
	global_load_lds_dwordx4 v[140:141], off
	v_lshl_add_u64 v[140:141], s[8:9], 0, v[132:133]
	s_mov_b32 m0, s85
	s_nop 0
	global_load_lds_dwordx4 v[140:141], off
	v_lshl_add_u64 v[140:141], s[8:9], 0, v[130:131]
	s_mov_b32 m0, s86
	s_nop 0
	global_load_lds_dwordx4 v[140:141], off
	v_lshl_add_u64 v[140:141], v[214:215], 0, s[4:5]
	s_mov_b32 m0, s83
	s_nop 0
	global_load_lds_dwordx4 v[140:141], off
	v_lshl_add_u64 v[140:141], v[216:217], 0, s[4:5]
	s_mov_b32 m0, s84
	s_nop 0
	global_load_lds_dwordx4 v[140:141], off
	s_add_i32 s91, s91, 2
	s_add_u32 s52, s52, 0x100
	s_addc_u32 s53, s53, 0
	s_add_u32 s89, s89, 0x100
	s_addc_u32 s90, s90, 0
	s_cmp_gt_u32 s91, 29
	s_waitcnt vmcnt(8)
	s_waitcnt lgkmcnt(0)
	s_setprio 1
	s_barrier
	v_mfma_f32_16x16x32_bf16 v[94:97], v[146:149], v[180:183], v[94:97]
	v_mfma_f32_16x16x32_bf16 v[86:89], v[154:157], v[180:183], v[86:89]
	v_mfma_f32_16x16x32_bf16 v[78:81], v[146:149], v[188:191], v[78:81]
	v_mfma_f32_16x16x32_bf16 v[70:73], v[154:157], v[188:191], v[70:73]
	v_mfma_f32_16x16x32_bf16 v[62:65], v[146:149], v[196:199], v[62:65]
	v_mfma_f32_16x16x32_bf16 v[54:57], v[154:157], v[196:199], v[54:57]
	v_mfma_f32_16x16x32_bf16 v[46:49], v[146:149], v[204:207], v[46:49]
	v_mfma_f32_16x16x32_bf16 v[38:41], v[154:157], v[204:207], v[38:41]
	v_mfma_f32_16x16x32_bf16 v[94:97], v[150:153], v[184:187], v[94:97]
	v_mfma_f32_16x16x32_bf16 v[86:89], v[158:161], v[184:187], v[86:89]
	v_mfma_f32_16x16x32_bf16 v[78:81], v[150:153], v[192:195], v[78:81]
	v_mfma_f32_16x16x32_bf16 v[70:73], v[158:161], v[192:195], v[70:73]
	v_mfma_f32_16x16x32_bf16 v[62:65], v[150:153], v[200:203], v[62:65]
	v_mfma_f32_16x16x32_bf16 v[54:57], v[158:161], v[200:203], v[54:57]
	v_mfma_f32_16x16x32_bf16 v[46:49], v[150:153], v[208:211], v[46:49]
	v_mfma_f32_16x16x32_bf16 v[38:41], v[158:161], v[208:211], v[38:41]
	s_setprio 0
	s_setprio 1
	v_mfma_f32_16x16x32_bf16 v[30:33], v[162:165], v[180:183], v[30:33]
	v_mfma_f32_16x16x32_bf16 v[26:29], v[170:173], v[180:183], v[26:29]
	v_mfma_f32_16x16x32_bf16 v[22:25], v[162:165], v[188:191], v[22:25]
	v_mfma_f32_16x16x32_bf16 v[18:21], v[170:173], v[188:191], v[18:21]
	v_mfma_f32_16x16x32_bf16 v[14:17], v[162:165], v[196:199], v[14:17]
	v_mfma_f32_16x16x32_bf16 v[10:13], v[170:173], v[196:199], v[10:13]
	v_mfma_f32_16x16x32_bf16 v[6:9], v[162:165], v[204:207], v[6:9]
	v_mfma_f32_16x16x32_bf16 v[2:5], v[170:173], v[204:207], v[2:5]
	v_mfma_f32_16x16x32_bf16 v[30:33], v[166:169], v[184:187], v[30:33]
	v_mfma_f32_16x16x32_bf16 v[26:29], v[174:177], v[184:187], v[26:29]
	v_mfma_f32_16x16x32_bf16 v[22:25], v[166:169], v[192:195], v[22:25]
	v_mfma_f32_16x16x32_bf16 v[18:21], v[174:177], v[192:195], v[18:21]
	v_mfma_f32_16x16x32_bf16 v[14:17], v[166:169], v[200:203], v[14:17]
	v_mfma_f32_16x16x32_bf16 v[10:13], v[174:177], v[200:203], v[10:13]
	v_mfma_f32_16x16x32_bf16 v[6:9], v[166:169], v[208:211], v[6:9]
	v_mfma_f32_16x16x32_bf16 v[2:5], v[174:177], v[208:211], v[2:5]
	s_barrier
	s_setprio 0
	s_cbranch_scc0 .LBB0_452
	s_and_b64 vcc, exec, s[6:7]
	s_cbranch_vccz .LBB0_455
	s_barrier

.LBB0_601:
	ds_read_b128 v[2:5], v200
	ds_read_b128 v[6:9], v200 offset:1024
	ds_read_b128 v[18:21], v200 offset:2048
	ds_read_b128 v[22:25], v200 offset:3072
	ds_read_b128 v[26:29], v200 offset:16384
	ds_read_b128 v[30:33], v200 offset:17408
	ds_read_b128 v[182:185], v200 offset:18432
	ds_read_b128 v[186:189], v200 offset:19456
	s_add_u32 s63, s80, 0xfffe0080
	s_addc_u32 s71, s81, -1
	s_cmp_eq_u32 s62, 4
	s_cselect_b32 s83, s4, s71
	s_cselect_b32 s82, s5, s63
	s_cselect_b32 s79, s53, s9
	s_cselect_b32 s78, s55, s8
	s_mov_b32 m0, s96
	v_lshl_add_u64 v[226:227], s[80:81], 0, v[170:171]
	ds_read_b128 v[10:13], v201
	ds_read_b128 v[14:17], v201 offset:1024
	ds_read_b128 v[202:205], v201 offset:2048
	ds_read_b128 v[206:209], v201 offset:3072
	ds_read_b128 v[210:213], v201 offset:4096
	ds_read_b128 v[214:217], v201 offset:5120
	ds_read_b128 v[218:221], v201 offset:6144
	ds_read_b128 v[222:225], v201 offset:7168
	global_load_lds_dwordx4 v[226:227], off
	v_lshl_add_u64 v[226:227], s[80:81], 0, v[172:173]
	s_mov_b32 m0, s61
	s_nop 0
	global_load_lds_dwordx4 v[226:227], off
	s_waitcnt vmcnt(8)
	s_waitcnt lgkmcnt(0)
	s_setprio 1
	s_barrier
	v_mfma_f32_16x16x128_f8f6f4 v[158:161], v[2:9], v[10:17], v[158:161]
	v_mfma_f32_16x16x128_f8f6f4 v[154:157], v[18:25], v[10:17], v[154:157]
	v_mfma_f32_16x16x128_f8f6f4 v[122:125], v[182:189], v[10:17], v[122:125]
	v_mfma_f32_16x16x128_f8f6f4 v[126:129], v[26:33], v[10:17], v[126:129]
	v_mfma_f32_16x16x128_f8f6f4 v[118:121], v[26:33], v[202:209], v[118:121]
	v_mfma_f32_16x16x128_f8f6f4 v[114:117], v[182:189], v[202:209], v[114:117]
	v_mfma_f32_16x16x128_f8f6f4 v[146:149], v[18:25], v[202:209], v[146:149]
	v_mfma_f32_16x16x128_f8f6f4 v[150:153], v[2:9], v[202:209], v[150:153]
	s_setprio 0
	s_setprio 1
	v_mfma_f32_16x16x128_f8f6f4 v[142:145], v[2:9], v[210:217], v[142:145]
	v_mfma_f32_16x16x128_f8f6f4 v[138:141], v[18:25], v[210:217], v[138:141]
	v_mfma_f32_16x16x128_f8f6f4 v[106:109], v[182:189], v[210:217], v[106:109]
	v_mfma_f32_16x16x128_f8f6f4 v[110:113], v[26:33], v[210:217], v[110:113]
	v_mfma_f32_16x16x128_f8f6f4 v[102:105], v[26:33], v[218:225], v[102:105]
	v_mfma_f32_16x16x128_f8f6f4 v[98:101], v[182:189], v[218:225], v[98:101]
	v_mfma_f32_16x16x128_f8f6f4 v[130:133], v[18:25], v[218:225], v[130:133]
	v_mfma_f32_16x16x128_f8f6f4 v[134:137], v[2:9], v[218:225], v[134:137]
	s_barrier
	s_setprio 0
	s_mov_b32 m0, s68
	v_lshl_add_u64 v[10:11], s[78:79], 0, v[164:165]
	s_add_u32 vcc_lo, s78, 0x20000
	ds_read_b128 v[202:205], v201 offset:16384
	ds_read_b128 v[206:209], v201 offset:17408
	ds_read_b128 v[210:213], v201 offset:18432
	ds_read_b128 v[214:217], v201 offset:19456
	ds_read_b128 v[218:221], v201 offset:20480
	ds_read_b128 v[222:225], v201 offset:21504
	ds_read_b128 v[226:229], v201 offset:22528
	ds_read_b128 v[230:233], v201 offset:23552
	global_load_lds_dwordx4 v[10:11], off
	v_lshl_add_u64 v[12:13], s[78:79], 0, v[168:169]
	s_mov_b32 m0, s69
	s_addc_u32 vcc_hi, s79, 0
	global_load_lds_dwordx4 v[12:13], off
	v_lshl_add_u64 v[14:15], vcc, 0, v[164:165]
	s_mov_b32 m0, s77
	v_lshl_add_u64 v[16:17], s[82:83], 0, v[166:167]
	global_load_lds_dwordx4 v[14:15], off
	v_lshl_add_u64 v[14:15], vcc, 0, v[168:169]
	s_mov_b32 m0, s84
	s_nop 0
	global_load_lds_dwordx4 v[14:15], off
	v_lshl_add_u64 v[14:15], s[82:83], 0, v[162:163]
	s_mov_b32 m0, s33
	s_nop 0
	global_load_lds_dwordx4 v[14:15], off
	s_mov_b32 m0, s85
	s_nop 0
	global_load_lds_dwordx4 v[16:17], off
	s_waitcnt vmcnt(8)
	s_waitcnt lgkmcnt(0)
	s_setprio 1
	s_barrier
	v_mfma_f32_16x16x128_f8f6f4 v[94:97], v[2:9], v[202:209], v[94:97]
	v_mfma_f32_16x16x128_f8f6f4 v[90:93], v[18:25], v[202:209], v[90:93]
	v_mfma_f32_16x16x128_f8f6f4 v[58:61], v[182:189], v[202:209], v[58:61]
	v_mfma_f32_16x16x128_f8f6f4 v[62:65], v[26:33], v[202:209], v[62:65]
	v_mfma_f32_16x16x128_f8f6f4 v[54:57], v[26:33], v[210:217], v[54:57]
	v_mfma_f32_16x16x128_f8f6f4 v[50:53], v[182:189], v[210:217], v[50:53]
	v_mfma_f32_16x16x128_f8f6f4 v[82:85], v[18:25], v[210:217], v[82:85]
	v_mfma_f32_16x16x128_f8f6f4 v[86:89], v[2:9], v[210:217], v[86:89]
	s_setprio 0
	s_setprio 1
	v_mfma_f32_16x16x128_f8f6f4 v[78:81], v[2:9], v[218:225], v[78:81]
	v_mfma_f32_16x16x128_f8f6f4 v[74:77], v[18:25], v[218:225], v[74:77]
	v_mfma_f32_16x16x128_f8f6f4 v[42:45], v[182:189], v[218:225], v[42:45]
	v_mfma_f32_16x16x128_f8f6f4 v[46:49], v[26:33], v[218:225], v[46:49]
	v_mfma_f32_16x16x128_f8f6f4 v[38:41], v[26:33], v[226:233], v[38:41]
	v_mfma_f32_16x16x128_f8f6f4 v[34:37], v[182:189], v[226:233], v[34:37]
	v_mfma_f32_16x16x128_f8f6f4 v[66:69], v[18:25], v[226:233], v[66:69]
	v_mfma_f32_16x16x128_f8f6f4 v[70:73], v[2:9], v[226:233], v[70:73]
	s_barrier
	s_setprio 0
	ds_read_b128 v[18:21], v200 offset:32768
	ds_read_b128 v[22:25], v200 offset:33792
	ds_read_b128 v[26:29], v200 offset:34816
	ds_read_b128 v[30:33], v200 offset:35840
	ds_read_b128 v[2:5], v200 offset:49152
	ds_read_b128 v[6:9], v200 offset:50176
	ds_read_b128 v[182:185], v200 offset:51200
	ds_read_b128 v[186:189], v200 offset:52224
	s_add_u32 s82, s82, 0x20000
	s_addc_u32 s83, s83, 0
	s_mov_b32 m0, s86
	v_lshl_add_u64 v[234:235], s[82:83], 0, v[162:163]
	ds_read_b128 v[202:205], v201 offset:32768
	ds_read_b128 v[206:209], v201 offset:33792
	ds_read_b128 v[210:213], v201 offset:34816
	ds_read_b128 v[214:217], v201 offset:35840
	ds_read_b128 v[218:221], v201 offset:36864
	ds_read_b128 v[222:225], v201 offset:37888
	ds_read_b128 v[226:229], v201 offset:38912
	ds_read_b128 v[230:233], v201 offset:39936
	global_load_lds_dwordx4 v[234:235], off
	v_lshl_add_u64 v[234:235], s[82:83], 0, v[166:167]
	s_mov_b32 m0, s87
	s_nop 0
	global_load_lds_dwordx4 v[234:235], off
	s_waitcnt vmcnt(8)
	s_waitcnt lgkmcnt(0)
	s_setprio 1
	s_barrier
	v_mfma_f32_16x16x128_f8f6f4 v[158:161], v[18:25], v[202:209], v[158:161]
	v_mfma_f32_16x16x128_f8f6f4 v[154:157], v[26:33], v[202:209], v[154:157]
	v_mfma_f32_16x16x128_f8f6f4 v[122:125], v[182:189], v[202:209], v[122:125]
	v_mfma_f32_16x16x128_f8f6f4 v[126:129], v[2:9], v[202:209], v[126:129]
	v_mfma_f32_16x16x128_f8f6f4 v[118:121], v[2:9], v[210:217], v[118:121]
	v_mfma_f32_16x16x128_f8f6f4 v[114:117], v[182:189], v[210:217], v[114:117]
	v_mfma_f32_16x16x128_f8f6f4 v[146:149], v[26:33], v[210:217], v[146:149]
	v_mfma_f32_16x16x128_f8f6f4 v[150:153], v[18:25], v[210:217], v[150:153]
	s_setprio 0
	s_setprio 1
	v_mfma_f32_16x16x128_f8f6f4 v[142:145], v[18:25], v[218:225], v[142:145]
	v_mfma_f32_16x16x128_f8f6f4 v[138:141], v[26:33], v[218:225], v[138:141]
	v_mfma_f32_16x16x128_f8f6f4 v[106:109], v[182:189], v[218:225], v[106:109]
	v_mfma_f32_16x16x128_f8f6f4 v[110:113], v[2:9], v[218:225], v[110:113]
	v_mfma_f32_16x16x128_f8f6f4 v[102:105], v[2:9], v[226:233], v[102:105]
	v_mfma_f32_16x16x128_f8f6f4 v[98:101], v[182:189], v[226:233], v[98:101]
	v_mfma_f32_16x16x128_f8f6f4 v[130:133], v[26:33], v[226:233], v[130:133]
	v_mfma_f32_16x16x128_f8f6f4 v[134:137], v[18:25], v[226:233], v[134:137]
	s_barrier
	s_setprio 0
	s_mov_b32 m0, s89
	v_lshl_add_u64 v[10:11], v[10:11], 0, s[42:43]
	s_add_u32 s78, s78, 0x20080
	ds_read_b128 v[202:205], v201 offset:49152
	ds_read_b128 v[206:209], v201 offset:50176
	ds_read_b128 v[210:213], v201 offset:51200
	ds_read_b128 v[214:217], v201 offset:52224
	ds_read_b128 v[218:221], v201 offset:53248
	ds_read_b128 v[222:225], v201 offset:54272
	ds_read_b128 v[226:229], v201 offset:55296
	ds_read_b128 v[230:233], v201 offset:56320
	global_load_lds_dwordx4 v[10:11], off
	v_lshl_add_u64 v[10:11], v[12:13], 0, s[42:43]
	s_mov_b32 m0, s90
	s_addc_u32 s79, s79, 0
	global_load_lds_dwordx4 v[10:11], off
	v_lshl_add_u64 v[10:11], s[78:79], 0, v[164:165]
	s_mov_b32 m0, s93
	s_nop 0
	global_load_lds_dwordx4 v[10:11], off
	v_lshl_add_u64 v[10:11], s[78:79], 0, v[168:169]
	s_mov_b32 m0, s95
	s_nop 0
	global_load_lds_dwordx4 v[10:11], off
	v_lshl_add_u64 v[10:11], v[14:15], 0, s[42:43]
	s_mov_b32 m0, s91
	s_nop 0
	global_load_lds_dwordx4 v[10:11], off
	v_lshl_add_u64 v[10:11], v[16:17], 0, s[42:43]
	s_mov_b32 m0, s92
	s_nop 0
	global_load_lds_dwordx4 v[10:11], off
	s_add_i32 s62, s62, 2
	s_add_u32 s80, s80, 0x100
	s_addc_u32 s81, s81, 0
	s_add_u32 s8, s8, 0x100
	s_addc_u32 s9, s9, 0
	s_cmp_gt_u32 s62, 5
	s_waitcnt vmcnt(8)
	s_waitcnt lgkmcnt(0)
	s_setprio 1
	s_barrier
	v_mfma_f32_16x16x128_f8f6f4 v[94:97], v[18:25], v[202:209], v[94:97]
	v_mfma_f32_16x16x128_f8f6f4 v[90:93], v[26:33], v[202:209], v[90:93]
	v_mfma_f32_16x16x128_f8f6f4 v[58:61], v[182:189], v[202:209], v[58:61]
	v_mfma_f32_16x16x128_f8f6f4 v[62:65], v[2:9], v[202:209], v[62:65]
	v_mfma_f32_16x16x128_f8f6f4 v[54:57], v[2:9], v[210:217], v[54:57]
	v_mfma_f32_16x16x128_f8f6f4 v[50:53], v[182:189], v[210:217], v[50:53]
	v_mfma_f32_16x16x128_f8f6f4 v[82:85], v[26:33], v[210:217], v[82:85]
	v_mfma_f32_16x16x128_f8f6f4 v[86:89], v[18:25], v[210:217], v[86:89]
	s_setprio 0
	s_setprio 1
	v_mfma_f32_16x16x128_f8f6f4 v[78:81], v[18:25], v[218:225], v[78:81]
	v_mfma_f32_16x16x128_f8f6f4 v[74:77], v[26:33], v[218:225], v[74:77]
	v_mfma_f32_16x16x128_f8f6f4 v[42:45], v[182:189], v[218:225], v[42:45]
	v_mfma_f32_16x16x128_f8f6f4 v[46:49], v[2:9], v[218:225], v[46:49]
	v_mfma_f32_16x16x128_f8f6f4 v[38:41], v[2:9], v[226:233], v[38:41]
	v_mfma_f32_16x16x128_f8f6f4 v[34:37], v[182:189], v[226:233], v[34:37]
	v_mfma_f32_16x16x128_f8f6f4 v[66:69], v[26:33], v[226:233], v[66:69]
	v_mfma_f32_16x16x128_f8f6f4 v[70:73], v[18:25], v[226:233], v[70:73]
	s_barrier
	s_setprio 0
	s_cbranch_scc0 .LBB0_601
	s_and_b64 vcc, exec, s[44:45]
	s_cbranch_vccz .LBB0_604
	s_barrier

.LBB0_947:
	ds_read_b128 v[2:5], v192
	ds_read_b128 v[6:9], v192 offset:1024
	ds_read_b128 v[18:21], v192 offset:2048
	ds_read_b128 v[22:25], v192 offset:3072
	ds_read_b128 v[26:29], v192 offset:16384
	ds_read_b128 v[30:33], v192 offset:17408
	ds_read_b128 v[184:187], v192 offset:18432
	ds_read_b128 v[188:191], v192 offset:19456
	s_add_u32 s44, s46, 0xfff80080
	s_addc_u32 s45, s47, -1
	s_cmp_eq_u32 s86, 28
	s_cselect_b32 s49, s37, s45
	s_cselect_b32 s48, s84, s44
	s_cselect_b32 s45, s27, s63
	s_cselect_b32 s44, s85, s62
	s_mov_b32 m0, s80
	v_lshl_add_u64 v[218:219], s[46:47], 0, v[172:173]
	ds_read_b128 v[10:13], v193
	ds_read_b128 v[14:17], v193 offset:1024
	ds_read_b128 v[194:197], v193 offset:2048
	ds_read_b128 v[198:201], v193 offset:3072
	ds_read_b128 v[202:205], v193 offset:4096
	ds_read_b128 v[206:209], v193 offset:5120
	ds_read_b128 v[210:213], v193 offset:6144
	ds_read_b128 v[214:217], v193 offset:7168
	global_load_lds_dwordx4 v[218:219], off
	v_lshl_add_u64 v[218:219], s[46:47], 0, v[174:175]
	s_mov_b32 m0, s81
	s_nop 0
	global_load_lds_dwordx4 v[218:219], off
	s_waitcnt vmcnt(8)
	s_waitcnt lgkmcnt(0)
	s_setprio 1
	s_barrier
	v_mfma_f32_16x16x128_f8f6f4 v[158:161], v[2:9], v[10:17], v[158:161]
	v_mfma_f32_16x16x128_f8f6f4 v[154:157], v[18:25], v[10:17], v[154:157]
	v_mfma_f32_16x16x128_f8f6f4 v[122:125], v[184:191], v[10:17], v[122:125]
	v_mfma_f32_16x16x128_f8f6f4 v[126:129], v[26:33], v[10:17], v[126:129]
	v_mfma_f32_16x16x128_f8f6f4 v[118:121], v[26:33], v[194:201], v[118:121]
	v_mfma_f32_16x16x128_f8f6f4 v[114:117], v[184:191], v[194:201], v[114:117]
	v_mfma_f32_16x16x128_f8f6f4 v[146:149], v[18:25], v[194:201], v[146:149]
	v_mfma_f32_16x16x128_f8f6f4 v[150:153], v[2:9], v[194:201], v[150:153]
	s_setprio 0
	s_setprio 1
	v_mfma_f32_16x16x128_f8f6f4 v[142:145], v[2:9], v[202:209], v[142:145]
	v_mfma_f32_16x16x128_f8f6f4 v[138:141], v[18:25], v[202:209], v[138:141]
	v_mfma_f32_16x16x128_f8f6f4 v[106:109], v[184:191], v[202:209], v[106:109]
	v_mfma_f32_16x16x128_f8f6f4 v[110:113], v[26:33], v[202:209], v[110:113]
	v_mfma_f32_16x16x128_f8f6f4 v[102:105], v[26:33], v[210:217], v[102:105]
	v_mfma_f32_16x16x128_f8f6f4 v[98:101], v[184:191], v[210:217], v[98:101]
	v_mfma_f32_16x16x128_f8f6f4 v[130:133], v[18:25], v[210:217], v[130:133]
	v_mfma_f32_16x16x128_f8f6f4 v[134:137], v[2:9], v[210:217], v[134:137]
	s_barrier
	s_setprio 0
	s_mov_b32 m0, s52
	v_lshl_add_u64 v[10:11], s[44:45], 0, v[166:167]
	s_add_u32 s88, s44, 0x80000
	ds_read_b128 v[194:197], v193 offset:16384
	ds_read_b128 v[198:201], v193 offset:17408
	ds_read_b128 v[202:205], v193 offset:18432
	ds_read_b128 v[206:209], v193 offset:19456
	ds_read_b128 v[210:213], v193 offset:20480
	ds_read_b128 v[214:217], v193 offset:21504
	ds_read_b128 v[218:221], v193 offset:22528
	ds_read_b128 v[222:225], v193 offset:23552
	global_load_lds_dwordx4 v[10:11], off
	v_lshl_add_u64 v[12:13], s[44:45], 0, v[170:171]
	s_mov_b32 m0, s53
	s_addc_u32 s89, s45, 0
	global_load_lds_dwordx4 v[12:13], off
	v_lshl_add_u64 v[14:15], s[88:89], 0, v[166:167]
	s_mov_b32 m0, s54
	v_lshl_add_u64 v[16:17], s[48:49], 0, v[168:169]
	global_load_lds_dwordx4 v[14:15], off
	v_lshl_add_u64 v[14:15], s[88:89], 0, v[170:171]
	s_mov_b32 m0, s55
	s_nop 0
	global_load_lds_dwordx4 v[14:15], off
	v_lshl_add_u64 v[14:15], s[48:49], 0, v[164:165]
	s_mov_b32 m0, s43
	s_nop 0
	global_load_lds_dwordx4 v[14:15], off
	s_mov_b32 m0, s61
	s_nop 0
	global_load_lds_dwordx4 v[16:17], off
	s_waitcnt vmcnt(8)
	s_waitcnt lgkmcnt(0)
	s_setprio 1
	s_barrier
	v_mfma_f32_16x16x128_f8f6f4 v[94:97], v[2:9], v[194:201], v[94:97]
	v_mfma_f32_16x16x128_f8f6f4 v[90:93], v[18:25], v[194:201], v[90:93]
	v_mfma_f32_16x16x128_f8f6f4 v[58:61], v[184:191], v[194:201], v[58:61]
	v_mfma_f32_16x16x128_f8f6f4 v[62:65], v[26:33], v[194:201], v[62:65]
	v_mfma_f32_16x16x128_f8f6f4 v[54:57], v[26:33], v[202:209], v[54:57]
	v_mfma_f32_16x16x128_f8f6f4 v[50:53], v[184:191], v[202:209], v[50:53]
	v_mfma_f32_16x16x128_f8f6f4 v[82:85], v[18:25], v[202:209], v[82:85]
	v_mfma_f32_16x16x128_f8f6f4 v[86:89], v[2:9], v[202:209], v[86:89]
	s_setprio 0
	s_setprio 1
	v_mfma_f32_16x16x128_f8f6f4 v[78:81], v[2:9], v[210:217], v[78:81]
	v_mfma_f32_16x16x128_f8f6f4 v[74:77], v[18:25], v[210:217], v[74:77]
	v_mfma_f32_16x16x128_f8f6f4 v[42:45], v[184:191], v[210:217], v[42:45]
	v_mfma_f32_16x16x128_f8f6f4 v[46:49], v[26:33], v[210:217], v[46:49]
	v_mfma_f32_16x16x128_f8f6f4 v[38:41], v[26:33], v[218:225], v[38:41]
	v_mfma_f32_16x16x128_f8f6f4 v[34:37], v[184:191], v[218:225], v[34:37]
	v_mfma_f32_16x16x128_f8f6f4 v[66:69], v[18:25], v[218:225], v[66:69]
	v_mfma_f32_16x16x128_f8f6f4 v[70:73], v[2:9], v[218:225], v[70:73]
	s_barrier
	s_setprio 0
	ds_read_b128 v[18:21], v192 offset:32768
	ds_read_b128 v[22:25], v192 offset:33792
	ds_read_b128 v[26:29], v192 offset:34816
	ds_read_b128 v[30:33], v192 offset:35840
	ds_read_b128 v[2:5], v192 offset:49152
	ds_read_b128 v[6:9], v192 offset:50176
	ds_read_b128 v[184:187], v192 offset:51200
	ds_read_b128 v[188:191], v192 offset:52224
	s_add_u32 s48, s48, 0x80000
	s_addc_u32 s49, s49, 0
	s_mov_b32 m0, s68
	v_lshl_add_u64 v[226:227], s[48:49], 0, v[164:165]
	ds_read_b128 v[194:197], v193 offset:32768
	ds_read_b128 v[198:201], v193 offset:33792
	ds_read_b128 v[202:205], v193 offset:34816
	ds_read_b128 v[206:209], v193 offset:35840
	ds_read_b128 v[210:213], v193 offset:36864
	ds_read_b128 v[214:217], v193 offset:37888
	ds_read_b128 v[218:221], v193 offset:38912
	ds_read_b128 v[222:225], v193 offset:39936
	global_load_lds_dwordx4 v[226:227], off
	v_lshl_add_u64 v[226:227], s[48:49], 0, v[168:169]
	s_mov_b32 m0, s69
	s_nop 0
	global_load_lds_dwordx4 v[226:227], off
	s_waitcnt vmcnt(8)
	s_waitcnt lgkmcnt(0)
	s_setprio 1
	s_barrier
	v_mfma_f32_16x16x128_f8f6f4 v[158:161], v[18:25], v[194:201], v[158:161]
	v_mfma_f32_16x16x128_f8f6f4 v[154:157], v[26:33], v[194:201], v[154:157]
	v_mfma_f32_16x16x128_f8f6f4 v[122:125], v[184:191], v[194:201], v[122:125]
	v_mfma_f32_16x16x128_f8f6f4 v[126:129], v[2:9], v[194:201], v[126:129]
	v_mfma_f32_16x16x128_f8f6f4 v[118:121], v[2:9], v[202:209], v[118:121]
	v_mfma_f32_16x16x128_f8f6f4 v[114:117], v[184:191], v[202:209], v[114:117]
	v_mfma_f32_16x16x128_f8f6f4 v[146:149], v[26:33], v[202:209], v[146:149]
	v_mfma_f32_16x16x128_f8f6f4 v[150:153], v[18:25], v[202:209], v[150:153]
	s_setprio 0
	s_setprio 1
	v_mfma_f32_16x16x128_f8f6f4 v[142:145], v[18:25], v[210:217], v[142:145]
	v_mfma_f32_16x16x128_f8f6f4 v[138:141], v[26:33], v[210:217], v[138:141]
	v_mfma_f32_16x16x128_f8f6f4 v[106:109], v[184:191], v[210:217], v[106:109]
	v_mfma_f32_16x16x128_f8f6f4 v[110:113], v[2:9], v[210:217], v[110:113]
	v_mfma_f32_16x16x128_f8f6f4 v[102:105], v[2:9], v[218:225], v[102:105]
	v_mfma_f32_16x16x128_f8f6f4 v[98:101], v[184:191], v[218:225], v[98:101]
	v_mfma_f32_16x16x128_f8f6f4 v[130:133], v[26:33], v[218:225], v[130:133]
	v_mfma_f32_16x16x128_f8f6f4 v[134:137], v[18:25], v[218:225], v[134:137]
	s_barrier
	s_setprio 0
	s_mov_b32 m0, s74
	v_lshl_add_u64 v[10:11], v[10:11], 0, s[4:5]
	s_add_u32 s44, s44, 0x80080
	ds_read_b128 v[194:197], v193 offset:49152
	ds_read_b128 v[198:201], v193 offset:50176
	ds_read_b128 v[202:205], v193 offset:51200
	ds_read_b128 v[206:209], v193 offset:52224
	ds_read_b128 v[210:213], v193 offset:53248
	ds_read_b128 v[214:217], v193 offset:54272
	ds_read_b128 v[218:221], v193 offset:55296
	ds_read_b128 v[222:225], v193 offset:56320
	global_load_lds_dwordx4 v[10:11], off
	v_lshl_add_u64 v[10:11], v[12:13], 0, s[4:5]
	s_mov_b32 m0, s75
	s_addc_u32 s45, s45, 0
	global_load_lds_dwordx4 v[10:11], off
	v_lshl_add_u64 v[10:11], s[44:45], 0, v[166:167]
	s_mov_b32 m0, s78
	s_nop 0
	global_load_lds_dwordx4 v[10:11], off
	v_lshl_add_u64 v[10:11], s[44:45], 0, v[170:171]
	s_mov_b32 m0, s79
	s_nop 0
	global_load_lds_dwordx4 v[10:11], off
	v_lshl_add_u64 v[10:11], v[14:15], 0, s[4:5]
	s_mov_b32 m0, s76
	s_nop 0
	global_load_lds_dwordx4 v[10:11], off
	v_lshl_add_u64 v[10:11], v[16:17], 0, s[4:5]
	s_mov_b32 m0, s77
	s_nop 0
	global_load_lds_dwordx4 v[10:11], off
	s_add_i32 s86, s86, 2
	s_add_u32 s46, s46, 0x100
	s_addc_u32 s47, s47, 0
	s_add_u32 s62, s62, 0x100
	s_addc_u32 s63, s63, 0
	s_cmp_gt_u32 s86, 29
	s_waitcnt vmcnt(8)
	s_waitcnt lgkmcnt(0)
	s_setprio 1
	s_barrier
	v_mfma_f32_16x16x128_f8f6f4 v[94:97], v[18:25], v[194:201], v[94:97]
	v_mfma_f32_16x16x128_f8f6f4 v[90:93], v[26:33], v[194:201], v[90:93]
	v_mfma_f32_16x16x128_f8f6f4 v[58:61], v[184:191], v[194:201], v[58:61]
	v_mfma_f32_16x16x128_f8f6f4 v[62:65], v[2:9], v[194:201], v[62:65]
	v_mfma_f32_16x16x128_f8f6f4 v[54:57], v[2:9], v[202:209], v[54:57]
	v_mfma_f32_16x16x128_f8f6f4 v[50:53], v[184:191], v[202:209], v[50:53]
	v_mfma_f32_16x16x128_f8f6f4 v[82:85], v[26:33], v[202:209], v[82:85]
	v_mfma_f32_16x16x128_f8f6f4 v[86:89], v[18:25], v[202:209], v[86:89]
	s_setprio 0
	s_setprio 1
	v_mfma_f32_16x16x128_f8f6f4 v[78:81], v[18:25], v[210:217], v[78:81]
	v_mfma_f32_16x16x128_f8f6f4 v[74:77], v[26:33], v[210:217], v[74:77]
	v_mfma_f32_16x16x128_f8f6f4 v[42:45], v[184:191], v[210:217], v[42:45]
	v_mfma_f32_16x16x128_f8f6f4 v[46:49], v[2:9], v[210:217], v[46:49]
	v_mfma_f32_16x16x128_f8f6f4 v[38:41], v[2:9], v[218:225], v[38:41]
	v_mfma_f32_16x16x128_f8f6f4 v[34:37], v[184:191], v[218:225], v[34:37]
	v_mfma_f32_16x16x128_f8f6f4 v[66:69], v[26:33], v[218:225], v[66:69]
	v_mfma_f32_16x16x128_f8f6f4 v[70:73], v[18:25], v[218:225], v[70:73]
	s_barrier
	s_setprio 0
	s_cbranch_scc0 .LBB0_947
	s_and_b64 vcc, exec, s[6:7]
	s_cbranch_vccz .LBB0_950
	s_barrier
